# strategy 4: static s_setprio 1 for waves 4-7 across the latent attention key loop
# speedup vs baseline: 1.0022x; 1.0022x over previous
.LBB0_887:
	v_add_f32_e32 v2, 0, v175
	v_add_f32_e32 v2, v176, v2
	v_add_f32_e32 v2, v177, v2
	v_add_f32_e32 v2, v178, v2
	v_add_f32_e32 v2, v179, v2
	v_add_f32_e32 v2, v180, v2
	v_add_f32_e32 v2, v181, v2
	v_add_f32_e32 v2, v182, v2
	v_add_f32_e32 v2, v183, v2
	v_add_f32_e32 v2, v184, v2
	v_add_f32_e32 v2, v185, v2
	v_add_f32_e32 v2, v186, v2
	v_add_f32_e32 v2, v187, v2
	v_add_f32_e32 v2, v188, v2
	v_add_f32_e32 v2, v189, v2
	v_add_f32_e32 v2, v190, v2
	v_add_f32_e32 v171, v14, v2
	v_exp_f32_e32 v2, v112
	v_exp_f32_e32 v4, v113
	v_exp_f32_e32 v5, v114
	v_exp_f32_e32 v14, v115
	v_add_f32_e32 v3, 0, v2
	v_exp_f32_e32 v112, v116
	v_add_f32_e32 v3, v4, v3
	v_exp_f32_e32 v113, v117
	v_add_f32_e32 v3, v5, v3
	v_exp_f32_e32 v114, v118
	v_add_f32_e32 v3, v14, v3
	v_exp_f32_e32 v115, v119
	v_add_f32_e32 v3, v112, v3
	v_exp_f32_e32 v116, v120
	v_add_f32_e32 v3, v113, v3
	v_exp_f32_e32 v117, v121
	v_add_f32_e32 v3, v114, v3
	v_exp_f32_e32 v118, v122
	v_add_f32_e32 v3, v115, v3
	v_exp_f32_e32 v119, v123
	v_add_f32_e32 v3, v116, v3
	v_exp_f32_e32 v120, v124
	v_add_f32_e32 v3, v117, v3
	v_exp_f32_e32 v121, v125
	v_add_f32_e32 v3, v118, v3
	v_exp_f32_e32 v122, v126
	v_add_f32_e32 v3, v119, v3
	v_exp_f32_e32 v123, v127
	v_add_f32_e32 v3, v120, v3
	v_add_f32_e32 v3, v121, v3
	v_add_f32_e32 v3, v122, v3
	v_add_f32_e32 v3, v123, v3
	v_add_f32_e32 v170, v15, v3
	v_cvt_pkrtz_f16_f32 v2, v2, v4
	v_cvt_pkrtz_f16_f32 v3, v5, v14
	v_cvt_pkrtz_f16_f32 v4, v112, v113
	v_cvt_pkrtz_f16_f32 v5, v114, v115
	v_mad_i64_i32 v[128:129], s[10:11], v142, s39, 0
	s_nop 0
	v_mfma_f32_32x32x16_f16 v[48:63], v[136:139], v[2:5], v[48:63]
	v_cvt_pkrtz_f16_f32 v112, v116, v117
	v_cvt_pkrtz_f16_f32 v113, v118, v119
	v_cvt_pkrtz_f16_f32 v114, v120, v121
	v_cvt_pkrtz_f16_f32 v115, v122, v123
	s_bfe_u32 s9, s28, 0x20006
	s_lshl_b32 s10, s9, 7
	s_mov_b32 s11, s59
	v_mfma_f32_32x32x16_f16 v[64:79], v[10:13], v[2:5], v[64:79]
	v_lshl_add_u64 v[2:3], v[140:141], 0, s[10:11]
	v_and_b32_e32 v4, 7, v144
	v_readlane_b32 s10, v255, 27
	v_lshlrev_b32_e32 v4, 4, v4
	v_mov_b32_e32 v5, v211
	s_add_u32 s4, s10, s4
	v_readlane_b32 s10, v255, 28
	v_mfma_f32_32x32x16_f16 v[48:63], v[132:135], v[112:115], v[48:63]
	s_mul_i32 s9, s9, 0x24000
	v_lshl_add_u64 v[2:3], v[2:3], 0, v[4:5]
	s_addc_u32 s5, s10, s5
	s_add_i32 s58, s58, s9
	v_lshl_add_u64 v[14:15], s[4:5], 0, v[2:3]
	s_lshl_b64 s[4:5], s[58:59], 1
	v_readlane_b32 s9, v255, 29
	v_mfma_f32_32x32x16_f16 v[64:79], v[6:9], v[112:115], v[64:79]
	s_waitcnt vmcnt(0)
	s_add_u32 s4, s9, s4
	v_readlane_b32 s9, v255, 30
	v_lshl_add_u64 v[2:3], v[128:129], 0, v[4:5]
	s_addc_u32 s5, s9, s5
	s_mov_b32 s12, 1
	v_lshl_add_u64 v[150:151], s[4:5], 0, v[2:3]
	s_mov_b32 s9, 1
	s_waitcnt vmcnt(0)
	s_barrier
	s_cmp_lt_u32 s3, 0x1000
	s_cbranch_scc1 .Lattn_prio_skip
	s_setprio 1
.Lattn_prio_skip:
.LBB0_888:
	s_add_i32 s4, s12, 1
	s_cmp_lg_u32 s12, 2
	s_cselect_b32 s10, s4, 0
	s_cmp_lt_u32 s9, 34
	s_mov_b64 s[4:5], -1
	s_cbranch_scc1 .LBB0_890
	s_lshl_b32 s11, s10, 14
	s_mov_b64 s[4:5], 0

.LBB0_902:
	s_setprio 0
	v_lshl_or_b32 v14, s10, 14, v159
	v_add_u32_e32 v10, v14, v158
	ds_read_b128 v[2:5], v157 offset:57344
	ds_read_b128 v[6:9], v157 offset:49152
	ds_read_b128 v[10:13], v10 offset:4096
	s_waitcnt lgkmcnt(0)
	s_nop 0
	v_mfma_f32_32x32x16_f16 v[112:127], v[10:13], v[6:9], v[194:209]
	v_add_u32_e32 v6, v14, v160
	ds_read_b128 v[6:9], v6 offset:4096
	v_max_f32_e32 v10, v81, v81
	v_max_f32_e32 v11, v80, v80
	v_max_f32_e32 v10, v11, v10
	v_max3_f32 v10, v10, v82, v83
	v_max3_f32 v10, v10, v84, v85
	v_max3_f32 v10, v10, v86, v87
	v_max3_f32 v10, v10, v88, v89
	v_max3_f32 v10, v10, v90, v91
	v_max3_f32 v10, v10, v92, v93
	v_max3_f32 v10, v10, v94, v95
	ds_bpermute_b32 v11, v153, v10
	s_waitcnt lgkmcnt(1)
	v_mfma_f32_32x32x16_f16 v[112:127], v[6:9], v[2:5], v[112:127]
	s_waitcnt lgkmcnt(0)
	v_max_f32_e32 v2, v11, v11
	v_max_f32_e32 v2, v10, v2
	v_cmp_lt_f32_e32 vcc, s61, v2
	s_cbranch_vccz .LBB0_904
	v_max_f32_e32 v2, v2, v2
	v_max_f32_e32 v2, 0, v2
	v_exp_f32_e64 v4, -v2
	v_pk_add_f32 v[80:81], v[80:81], v[2:3] op_sel_hi:[1,0] neg_lo:[0,1] neg_hi:[0,1]
	v_pk_add_f32 v[82:83], v[82:83], v[2:3] op_sel_hi:[1,0] neg_lo:[0,1] neg_hi:[0,1]
	v_pk_add_f32 v[84:85], v[84:85], v[2:3] op_sel_hi:[1,0] neg_lo:[0,1] neg_hi:[0,1]
	v_mul_f32_e32 v171, v171, v4
	v_pk_add_f32 v[86:87], v[86:87], v[2:3] op_sel_hi:[1,0] neg_lo:[0,1] neg_hi:[0,1]
	v_pk_add_f32 v[88:89], v[88:89], v[2:3] op_sel_hi:[1,0] neg_lo:[0,1] neg_hi:[0,1]
	v_pk_add_f32 v[90:91], v[90:91], v[2:3] op_sel_hi:[1,0] neg_lo:[0,1] neg_hi:[0,1]
	v_pk_add_f32 v[92:93], v[92:93], v[2:3] op_sel_hi:[1,0] neg_lo:[0,1] neg_hi:[0,1]
	v_pk_add_f32 v[94:95], v[94:95], v[2:3] op_sel_hi:[1,0] neg_lo:[0,1] neg_hi:[0,1]
	v_sub_f32_e32 v127, v127, v2
	v_sub_f32_e32 v126, v126, v2
	v_sub_f32_e32 v125, v125, v2
	v_sub_f32_e32 v124, v124, v2
	v_sub_f32_e32 v123, v123, v2
	v_sub_f32_e32 v122, v122, v2
	v_sub_f32_e32 v121, v121, v2
	v_sub_f32_e32 v120, v120, v2
	v_sub_f32_e32 v119, v119, v2
	v_sub_f32_e32 v118, v118, v2
	v_sub_f32_e32 v117, v117, v2
	v_sub_f32_e32 v116, v116, v2
	v_sub_f32_e32 v115, v115, v2
	v_sub_f32_e32 v114, v114, v2
	v_sub_f32_e32 v113, v113, v2
	v_sub_f32_e32 v112, v112, v2
	v_pk_mul_f32 v[30:31], v[30:31], v[4:5] op_sel_hi:[1,0]
	v_pk_mul_f32 v[28:29], v[28:29], v[4:5] op_sel_hi:[1,0]
	v_pk_mul_f32 v[26:27], v[26:27], v[4:5] op_sel_hi:[1,0]
	v_pk_mul_f32 v[24:25], v[24:25], v[4:5] op_sel_hi:[1,0]
	v_pk_mul_f32 v[22:23], v[22:23], v[4:5] op_sel_hi:[1,0]
	v_pk_mul_f32 v[20:21], v[20:21], v[4:5] op_sel_hi:[1,0]
	v_pk_mul_f32 v[18:19], v[18:19], v[4:5] op_sel_hi:[1,0]
	v_pk_mul_f32 v[16:17], v[16:17], v[4:5] op_sel_hi:[1,0]
	v_pk_mul_f32 v[46:47], v[46:47], v[4:5] op_sel_hi:[1,0]
	v_pk_mul_f32 v[44:45], v[44:45], v[4:5] op_sel_hi:[1,0]
	v_pk_mul_f32 v[42:43], v[42:43], v[4:5] op_sel_hi:[1,0]
	v_pk_mul_f32 v[40:41], v[40:41], v[4:5] op_sel_hi:[1,0]
	v_pk_mul_f32 v[38:39], v[38:39], v[4:5] op_sel_hi:[1,0]
	v_pk_mul_f32 v[36:37], v[36:37], v[4:5] op_sel_hi:[1,0]
	v_pk_mul_f32 v[34:35], v[34:35], v[4:5] op_sel_hi:[1,0]
	v_pk_mul_f32 v[32:33], v[32:33], v[4:5] op_sel_hi:[1,0]
